# P9 sample rows rewritten: per (batch,128-col) block, the two P8 half-K partials summed once and u rows shared through LDS; also writes s_ffn_conv rows
# speedup vs baseline: 1.0106x; 1.0058x over previous
.LBB0_1212:
	s_or_b64 exec, exec, s[34:35]
	v_lshrrev_b32_e32 v2, 5, v1
	v_and_b32_e32 v3, 31, v1
	v_lshlrev_b32_e32 v4, 4, v3
	v_mov_b32_e32 v21, 0
	v_mov_b32_e32 v31, 0
	v_mov_b32_e32 v17, 0
	v_mov_b32_e32 v19, 0
	v_mul_u32_u24_e32 v20, 0xb000, v2
	v_add_u32_e32 v20, v20, v4
	v_lshl_add_u32 v6, v2, 9, v4
	v_add_u32_e32 v6, 0x1000, v6
	v_mul_u32_u24_e32 v16, 0x2c00, v2
	v_lshl_add_u32 v16, v3, 3, v16
	v_add_u32_e32 v18, -14, v2
	v_and_b32_e32 v18, 1, v18
	v_mul_u32_u24_e32 v18, 0xb000, v18
	v_add_u32_e32 v18, v18, v4
	v_cmp_eq_u32_e64 s[92:93], 0, v2
	v_cmp_eq_u32_e64 s[94:95], 1, v2
	v_readfirstlane_b32 s30, v1
	s_lshr_b32 s30, s30, 6
	s_mov_b32 s88, 0x5800
	s_mov_b32 s89, 0
	s_mov_b32 s90, 0x1600000
	s_mov_b32 s91, 0
	s_mov_b32 s31, 0
	s_mov_b32 s84, s2
	s_cmpk_ge_u32 s84, 0x580
	s_cbranch_scc1 .Lp9s_done
	s_and_b32 s96, s84, 31
	s_lshr_b32 s97, s84, 5
	s_mul_i32 s96, s96, 0xb0000
	s_lshl_b32 s97, s97, 9
	s_add_i32 s96, s96, s97
	s_add_u32 s86, s18, s96
	s_addc_u32 s87, s19, 0
	v_lshl_add_u64 v[8:9], s[86:87], 0, v[20:21]
	global_load_dwordx4 v[32:35], v[8:9], off
	v_lshl_add_u64 v[10:11], v[8:9], 0, s[88:89]
	global_load_dwordx4 v[36:39], v[10:11], off
	v_lshl_add_u64 v[12:13], v[8:9], 0, s[90:91]
	global_load_dwordx4 v[40:43], v[12:13], off
	v_lshl_add_u64 v[14:15], v[10:11], 0, s[90:91]
	global_load_dwordx4 v[44:47], v[14:15], off
.Lp9s_loop:
	s_and_b32 s4, s84, 31
	s_lshr_b32 s5, s84, 5
	s_lshl_b32 s7, s5, 9
	v_add_u32_e32 v30, s7, v4
	v_lshl_add_u64 v[8:9], s[26:27], 0, v[30:31]
	global_load_dwordx4 v[56:59], v[8:9], off
	v_lshl_add_u64 v[8:9], v[8:9], 0, s[88:89]
	global_load_dwordx4 v[60:63], v[8:9], off
	v_lshl_add_u64 v[8:9], s[28:29], 0, v[30:31]
	global_load_dwordx4 v[64:67], v[8:9], off
	v_lshl_add_u64 v[8:9], v[8:9], 0, s[88:89]
	global_load_dwordx4 v[68:71], v[8:9], off
	v_lshl_add_u64 v[8:9], s[12:13], 0, v[30:31]
	global_load_dwordx4 v[72:75], v[8:9], off
	v_lshl_add_u64 v[8:9], v[8:9], 0, s[88:89]
	global_load_dwordx4 v[76:79], v[8:9], off
	v_lshl_add_u64 v[8:9], s[14:15], 0, v[30:31]
	global_load_dwordx4 v[80:83], v[8:9], off
	v_lshl_add_u64 v[8:9], v[8:9], 0, s[88:89]
	global_load_dwordx4 v[84:87], v[8:9], off
	s_cmp_lg_u32 s30, 0
	s_cbranch_scc1 .Lp9s_nostate
	s_mul_i32 s6, s4, 0x16000
	s_add_u32 s34, s24, s6
	s_addc_u32 s35, s25, 0
	v_lshl_add_u64 v[8:9], s[34:35], 0, v[30:31]
	global_load_dwordx4 v[96:99], v[8:9], off
	v_lshl_add_u64 v[8:9], v[8:9], 0, s[88:89]
	global_load_dwordx4 v[100:103], v[8:9], off
	v_lshl_add_u64 v[8:9], v[8:9], 0, s[88:89]
	global_load_dwordx4 v[88:91], v[8:9], off
	v_lshl_add_u64 v[8:9], v[8:9], 0, s[88:89]
	global_load_dwordx4 v[92:95], v[8:9], off
.Lp9s_nostate:
	s_waitcnt vmcnt(0)
	v_pk_add_f32 v[104:105], v[32:33], v[40:41]
	v_pk_add_f32 v[106:107], v[34:35], v[42:43]
	v_pk_add_f32 v[108:109], v[36:37], v[44:45]
	v_pk_add_f32 v[110:111], v[38:39], v[46:47]
	v_add_u32_e32 v7, s31, v6
	s_nop 0
	ds_write_b128 v7, v[104:107]
	ds_write_b128 v7, v[108:111] offset:8192
	s_add_i32 s85, s84, s33
	s_cmpk_ge_u32 s85, 0x580
	s_cbranch_scc1 .Lp9s_nopf
	s_and_b32 s96, s85, 31
	s_lshr_b32 s97, s85, 5
	s_mul_i32 s96, s96, 0xb0000
	s_lshl_b32 s97, s97, 9
	s_add_i32 s96, s96, s97
	s_add_u32 s86, s18, s96
	s_addc_u32 s87, s19, 0
	v_lshl_add_u64 v[8:9], s[86:87], 0, v[20:21]
	global_load_dwordx4 v[32:35], v[8:9], off
	v_lshl_add_u64 v[10:11], v[8:9], 0, s[88:89]
	global_load_dwordx4 v[36:39], v[10:11], off
	v_lshl_add_u64 v[12:13], v[8:9], 0, s[90:91]
	global_load_dwordx4 v[40:43], v[12:13], off
	v_lshl_add_u64 v[14:15], v[10:11], 0, s[90:91]
	global_load_dwordx4 v[44:47], v[14:15], off
.Lp9s_nopf:
	s_waitcnt lgkmcnt(0)
	s_barrier
	v_add_u32_e32 v5, 0xfffffc00, v7
	s_nop 0
	ds_read_b128 v[120:123], v5
	ds_read_b128 v[112:115], v5 offset:512
	ds_read_b128 v[124:127], v5 offset:8192
	ds_read_b128 v[116:119], v5 offset:8704
	s_waitcnt lgkmcnt(0)
	s_cmp_lg_u32 s30, 0
	s_cbranch_scc1 .Lp9s_nosel
	v_cndmask_b32_e64 v112, v112, v88, s[92:93]
	v_cndmask_b32_e64 v116, v116, v92, s[92:93]
	v_cndmask_b32_e64 v120, v120, v88, s[94:95]
	v_cndmask_b32_e64 v124, v124, v92, s[94:95]
	v_cndmask_b32_e64 v113, v113, v89, s[92:93]
	v_cndmask_b32_e64 v117, v117, v93, s[92:93]
	v_cndmask_b32_e64 v121, v121, v89, s[94:95]
	v_cndmask_b32_e64 v125, v125, v93, s[94:95]
	v_cndmask_b32_e64 v114, v114, v90, s[92:93]
	v_cndmask_b32_e64 v118, v118, v94, s[92:93]
	v_cndmask_b32_e64 v122, v122, v90, s[94:95]
	v_cndmask_b32_e64 v126, v126, v94, s[94:95]
	v_cndmask_b32_e64 v115, v115, v91, s[92:93]
	v_cndmask_b32_e64 v119, v119, v95, s[92:93]
	v_cndmask_b32_e64 v123, v123, v91, s[94:95]
	v_cndmask_b32_e64 v127, v127, v95, s[94:95]
	v_cndmask_b32_e64 v120, v120, v96, s[92:93]
	v_cndmask_b32_e64 v124, v124, v100, s[92:93]
	v_cndmask_b32_e64 v121, v121, v97, s[92:93]
	v_cndmask_b32_e64 v125, v125, v101, s[92:93]
	v_cndmask_b32_e64 v122, v122, v98, s[92:93]
	v_cndmask_b32_e64 v126, v126, v102, s[92:93]
	v_cndmask_b32_e64 v123, v123, v99, s[92:93]
	v_cndmask_b32_e64 v127, v127, v103, s[92:93]
.Lp9s_nosel:
	v_pk_mul_f32 v[128:129], v[112:113], v[64:65]
	v_pk_mul_f32 v[130:131], v[114:115], v[66:67]
	v_pk_mul_f32 v[132:133], v[116:117], v[68:69]
	v_pk_mul_f32 v[134:135], v[118:119], v[70:71]
	v_pk_fma_f32 v[128:129], v[104:105], v[56:57], v[128:129]
	v_pk_fma_f32 v[130:131], v[106:107], v[58:59], v[130:131]
	v_pk_fma_f32 v[132:133], v[108:109], v[60:61], v[132:133]
	v_pk_fma_f32 v[134:135], v[110:111], v[62:63], v[134:135]
	v_pk_fma_f32 v[128:129], v[120:121], v[72:73], v[128:129]
	v_pk_fma_f32 v[130:131], v[122:123], v[74:75], v[130:131]
	v_pk_fma_f32 v[132:133], v[124:125], v[76:77], v[132:133]
	v_pk_fma_f32 v[134:135], v[126:127], v[78:79], v[134:135]
	v_pk_add_f32 v[128:129], v[80:81], v[128:129]
	v_pk_add_f32 v[130:131], v[82:83], v[130:131]
	v_pk_add_f32 v[132:133], v[84:85], v[132:133]
	v_pk_add_f32 v[134:135], v[86:87], v[134:135]
	v_mul_f32_e32 v8, 0xbfb8aa3b, v128
	v_mul_f32_e32 v9, 0xbfb8aa3b, v129
	v_mul_f32_e32 v10, 0xbfb8aa3b, v130
	v_mul_f32_e32 v11, 0xbfb8aa3b, v131
	v_exp_f32_e32 v8, v8
	v_exp_f32_e32 v9, v9
	v_exp_f32_e32 v10, v10
	v_exp_f32_e32 v11, v11
	s_nop 0
	v_add_f32_e32 v8, 1.0, v8
	v_add_f32_e32 v9, 1.0, v9
	v_add_f32_e32 v10, 1.0, v10
	v_add_f32_e32 v11, 1.0, v11
	v_rcp_f32_e32 v8, v8
	v_rcp_f32_e32 v9, v9
	v_rcp_f32_e32 v10, v10
	v_rcp_f32_e32 v11, v11
	s_nop 1
	v_pk_mul_f32 v[128:129], v[128:129], v[8:9]
	v_pk_mul_f32 v[130:131], v[130:131], v[10:11]
	v_pk_mul_f32 v[128:129], v[128:129], v[132:133]
	v_pk_mul_f32 v[130:131], v[130:131], v[134:135]
	s_lshl_b32 s6, s4, 4
	s_add_i32 s6, s6, 0x4000
	s_mul_i32 s6, s6, 0x2c00
	s_lshl_b32 s7, s5, 8
	s_add_i32 s6, s6, s7
	s_add_u32 s38, s10, s6
	s_addc_u32 s39, s11, 0
	v_cvt_pk_bf16_f32 v12, v128, v129
	v_cvt_pk_bf16_f32 v13, v130, v131
	v_lshl_add_u64 v[14:15], s[38:39], 0, v[16:17]
	global_store_dwordx2 v[14:15], v[12:13], off
	s_cmp_lg_u32 s30, 7
	s_cbranch_scc1 .Lp9s_nosf
	s_mul_i32 s6, s4, 0x16000
	s_lshl_b32 s7, s5, 9
	s_add_i32 s6, s6, s7
	s_add_u32 s40, s8, 0xa09c000
	s_addc_u32 s41, s9, 0
	s_add_u32 s40, s40, s6
	s_addc_u32 s41, s41, 0
	v_lshl_add_u64 v[14:15], s[40:41], 0, v[18:19]
	global_store_dwordx4 v[14:15], v[104:107], off
	v_lshl_add_u64 v[14:15], v[14:15], 0, s[88:89]
	global_store_dwordx4 v[14:15], v[108:111], off
.Lp9s_nosf:
	s_xor_b32 s31, s31, 0x4000
	s_mov_b32 s84, s85
	s_cmpk_lt_u32 s84, 0x580
	s_cbranch_scc1 .Lp9s_loop
.Lp9s_done:
.LBB0_1214:
	s_or_b64 exec, exec, s[22:23]
	s_movk_i32 s4, 0x5800
	v_cmp_gt_i32_e32 vcc, s4, v54
	s_and_saveexec_b64 s[4:5], vcc
	s_cbranch_execz .LBB0_1217
	s_add_u32 s6, s8, 0x8724000
	v_lshlrev_b32_e32 v2, 2, v1
	s_addc_u32 s7, s9, 0
	v_lshl_add_u32 v6, s2, 11, v2
	s_lshl_b32 s12, s3, 2
	s_mov_b64 s[10:11], 0
	s_mov_b32 s13, 0x2e8ba2e9
	s_movk_i32 s14, 0x7e
	s_mov_b32 s15, 0xb000
	v_mov_b64_e32 v[2:3], s[20:21]
	s_movk_i32 s20, 0x57ff
	v_mov_b32_e32 v4, v54

.LBB0_1217:
	s_or_b64 exec, exec, s[4:5]
	s_mov_b32 s4, 0x2c000
	v_cmp_gt_i32_e32 vcc, s4, v54
	s_and_saveexec_b64 s[4:5], vcc
	s_cbranch_execz .LBB0_1220
.LBB0_1220:
	s_or_b64 exec, exec, s[4:5]
